# same as the rotated version with one missing wait state restored (128-bit store data overwritten one slot too early after two zero moves were merged)
# baseline (speedup 1.0000x reference)
.LBB0_782:
	s_or_b64 exec, exec, s[10:11]
	s_nop 0
	v_mov_b32_e32 v40, v198
	v_mov_b32_e32 v41, v198
	v_pk_mul_f32 v[44:45], v[22:23], v[40:41]
	v_pk_mul_f32 v[40:41], v[18:19], v[40:41]
	v_pk_mul_f32 v[18:19], v[24:25], v[196:197] op_sel_hi:[1,0]
	v_mov_b32_e32 v24, v194
	v_mov_b32_e32 v25, v194
	v_pk_mul_f32 v[6:7], v[6:7], v[24:25]
	v_pk_mul_f32 v[2:3], v[2:3], v[24:25]
	v_mov_b32_e32 v24, 0
	v_mov_b32_e32 v25, 0
	v_mov_b32_e32 v199, v198
	v_mov_b32_dpp v24, v92 row_ror:1 row_mask:0xf bank_mask:0xf
	v_mov_b32_dpp v25, v93 row_ror:1 row_mask:0xf bank_mask:0xf
	v_pk_mul_f32 v[42:43], v[16:17], v[198:199]
	v_pk_mul_f32 v[22:23], v[28:29], v[196:197] op_sel_hi:[1,0]
	v_pk_mul_f32 v[16:17], v[26:27], v[196:197] op_sel_hi:[1,0]
	v_mov_b64_e32 v[26:27], 0
	v_mov_b64_e32 v[28:29], 0
	v_mov_b32_dpp v24, v116 row_shr:1 row_mask:0xf bank_mask:0xf
	v_mov_b32_dpp v25, v117 row_shr:1 row_mask:0xf bank_mask:0xf
	v_mov_b32_dpp v26, v94 row_ror:1 row_mask:0xf bank_mask:0xf
	v_mov_b32_dpp v27, v95 row_ror:1 row_mask:0xf bank_mask:0xf
	v_mov_b32_dpp v28, v22 row_ror:15 row_mask:0xf bank_mask:0xf
	v_mov_b32_dpp v29, v23 row_ror:15 row_mask:0xf bank_mask:0xf
	v_pk_fma_f32 v[24:25], v[80:81], v[24:25], v[84:85]
	v_pk_mul_f32 v[46:47], v[20:21], v[198:199]
	v_pk_mul_f32 v[20:21], v[30:31], v[196:197] op_sel_hi:[1,0]
	v_mov_b64_e32 v[30:31], 0
	v_mov_b32_dpp v26, v114 row_shr:1 row_mask:0xf bank_mask:0xf
	v_mov_b32_dpp v27, v115 row_shr:1 row_mask:0xf bank_mask:0xf
	v_mov_b32_dpp v28, v116 row_shl:1 row_mask:0xf bank_mask:0xf
	v_mov_b32_dpp v29, v117 row_shl:1 row_mask:0xf bank_mask:0xf
	v_pk_fma_f32 v[24:25], v[116:117], v[76:77], v[24:25]
	v_mov_b32_dpp v30, v20 row_ror:15 row_mask:0xf bank_mask:0xf
	v_mov_b32_dpp v31, v21 row_ror:15 row_mask:0xf bank_mask:0xf
	v_pk_fma_f32 v[26:27], v[82:83], v[26:27], v[86:87]
	v_pk_fma_f32 v[24:25], v[72:73], v[28:29], v[24:25]
	v_mov_b32_dpp v30, v114 row_shl:1 row_mask:0xf bank_mask:0xf
	v_mov_b32_dpp v31, v115 row_shl:1 row_mask:0xf bank_mask:0xf
	v_pk_fma_f32 v[26:27], v[114:115], v[78:79], v[26:27]
	v_pk_mul_f32 v[28:29], v[24:25], v[24:25]
	v_pk_fma_f32 v[26:27], v[74:75], v[30:31], v[26:27]
	v_pk_mul_f32 v[28:29], v[24:25], v[28:29]
	v_pk_mul_f32 v[30:31], v[26:27], v[26:27]
	v_pk_fma_f32 v[28:29], v[28:29], s[70:71], v[24:25] op_sel_hi:[1,0,1]
	v_pk_mul_f32 v[30:31], v[26:27], v[30:31]
	v_pk_mul_f32 v[28:29], v[28:29], s[72:73] op_sel_hi:[1,0]
	v_pk_fma_f32 v[30:31], v[30:31], s[70:71], v[26:27] op_sel_hi:[1,0,1]
	v_min_f32_e32 v28, 0x41e6d4ca, v28
	v_pk_mul_f32 v[30:31], v[30:31], s[72:73] op_sel_hi:[1,0]
	v_exp_f32_e32 v49, v28
	v_min_f32_e32 v28, 0x41e6d4ca, v29
	v_exp_f32_e32 v48, v28
	v_min_f32_e32 v28, 0x41e6d4ca, v30
	v_exp_f32_e32 v29, v28
	v_min_f32_e32 v28, 0x41e6d4ca, v31
	v_exp_f32_e32 v28, v28
	v_pk_add_f32 v[30:31], v[48:49], 1.0 op_sel_hi:[1,0]
	v_add_u32_e32 v52, 0x90, v197
	v_pk_add_f32 v[28:29], v[28:29], 1.0 op_sel_hi:[1,0]
	v_mul_f32_e32 v48, v31, v30
	v_mul_f32_e32 v49, v29, v28
	v_pk_mul_f32 v[12:13], v[12:13], v[196:197] op_sel_hi:[1,0]
	v_mul_f32_e32 v50, v48, v49
	v_rcp_f32_e32 v51, v50
	v_pk_mul_f32 v[14:15], v[14:15], v[196:197] op_sel_hi:[1,0]
	v_pk_mul_f32 v[10:11], v[10:11], v[196:197] op_sel_hi:[1,0]
	v_pk_mul_f32 v[8:9], v[8:9], v[196:197] op_sel_hi:[1,0]
	v_mul_f32_e32 v48, v48, v51
	v_pk_mul_f32 v[28:29], v[28:29], v[48:49] op_sel_hi:[1,0]
	v_mul_f32_e32 v50, v49, v51
	v_pk_mul_f32 v[26:27], v[26:27], v[28:29]
	v_pk_mul_f32 v[30:31], v[30:31], v[50:51] op_sel_hi:[1,0]
	v_pk_mul_f32 v[28:29], v[44:45], v[26:27]
	v_mov_b32_e32 v26, 0
	v_mov_b32_e32 v27, 0
	v_pk_mul_f32 v[24:25], v[24:25], v[30:31]
	v_mov_b32_dpp v26, v88 row_ror:1 row_mask:0xf bank_mask:0xf
	v_mov_b32_dpp v27, v89 row_ror:1 row_mask:0xf bank_mask:0xf
	v_mov_b64_e32 v[30:31], 0
	v_mov_b64_e32 v[44:45], 0
	v_mov_b32_dpp v26, v110 row_shr:1 row_mask:0xf bank_mask:0xf
	v_mov_b32_dpp v27, v111 row_shr:1 row_mask:0xf bank_mask:0xf
	v_mov_b32_dpp v30, v90 row_ror:1 row_mask:0xf bank_mask:0xf
	v_mov_b32_dpp v31, v91 row_ror:1 row_mask:0xf bank_mask:0xf
	v_mov_b32_dpp v44, v18 row_ror:15 row_mask:0xf bank_mask:0xf
	v_mov_b32_dpp v45, v19 row_ror:15 row_mask:0xf bank_mask:0xf
	v_pk_fma_f32 v[26:27], v[64:65], v[26:27], v[68:69]
	v_pk_mul_f32 v[24:25], v[46:47], v[24:25]
	v_mov_b64_e32 v[46:47], 0
	v_mov_b32_dpp v30, v108 row_shr:1 row_mask:0xf bank_mask:0xf
	v_mov_b32_dpp v31, v109 row_shr:1 row_mask:0xf bank_mask:0xf
	v_mov_b32_dpp v44, v110 row_shl:1 row_mask:0xf bank_mask:0xf
	v_mov_b32_dpp v45, v111 row_shl:1 row_mask:0xf bank_mask:0xf
	v_pk_fma_f32 v[26:27], v[110:111], v[60:61], v[26:27]
	v_mov_b32_dpp v46, v16 row_ror:15 row_mask:0xf bank_mask:0xf
	v_mov_b32_dpp v47, v17 row_ror:15 row_mask:0xf bank_mask:0xf
	v_pk_fma_f32 v[30:31], v[66:67], v[30:31], v[70:71]
	v_pk_fma_f32 v[26:27], v[56:57], v[44:45], v[26:27]
	v_mov_b32_dpp v46, v108 row_shl:1 row_mask:0xf bank_mask:0xf
	v_mov_b32_dpp v47, v109 row_shl:1 row_mask:0xf bank_mask:0xf
	v_pk_fma_f32 v[30:31], v[108:109], v[62:63], v[30:31]
	v_pk_mul_f32 v[44:45], v[26:27], v[26:27]
	v_pk_fma_f32 v[30:31], v[58:59], v[46:47], v[30:31]
	v_pk_mul_f32 v[44:45], v[26:27], v[44:45]
	v_pk_mul_f32 v[46:47], v[30:31], v[30:31]
	v_pk_fma_f32 v[44:45], v[44:45], s[70:71], v[26:27] op_sel_hi:[1,0,1]
	v_pk_mul_f32 v[46:47], v[30:31], v[46:47]
	v_pk_mul_f32 v[44:45], v[44:45], s[72:73] op_sel_hi:[1,0]
	v_pk_fma_f32 v[46:47], v[46:47], s[70:71], v[30:31] op_sel_hi:[1,0,1]
	v_min_f32_e32 v44, 0x41e6d4ca, v44
	v_pk_mul_f32 v[46:47], v[46:47], s[72:73] op_sel_hi:[1,0]
	v_exp_f32_e32 v49, v44
	v_min_f32_e32 v44, 0x41e6d4ca, v45
	v_exp_f32_e32 v48, v44
	v_min_f32_e32 v44, 0x41e6d4ca, v46
	v_exp_f32_e32 v45, v44
	v_min_f32_e32 v44, 0x41e6d4ca, v47
	v_exp_f32_e32 v44, v44
	v_pk_add_f32 v[46:47], v[48:49], 1.0 op_sel_hi:[1,0]
	v_mov_b32_dpp v100, v36 row_shl:1 row_mask:0xf bank_mask:0xf
	v_pk_add_f32 v[44:45], v[44:45], 1.0 op_sel_hi:[1,0]
	v_mul_f32_e32 v48, v47, v46
	v_mul_f32_e32 v49, v45, v44
	v_mov_b32_dpp v101, v37 row_shl:1 row_mask:0xf bank_mask:0xf
	v_mul_f32_e32 v50, v48, v49
	v_rcp_f32_e32 v51, v50
	v_mov_b32_dpp v102, v38 row_shl:1 row_mask:0xf bank_mask:0xf
	v_mov_b32_dpp v103, v39 row_shl:1 row_mask:0xf bank_mask:0xf
	v_pk_mul_f32 v[4:5], v[4:5], v[194:195]
	v_mul_f32_e32 v50, v49, v51
	v_mul_f32_e32 v48, v48, v51
	v_pk_mul_f32 v[44:45], v[44:45], v[48:49] op_sel_hi:[1,0]
	v_pk_mul_f32 v[46:47], v[46:47], v[50:51] op_sel_hi:[1,0]
	v_pk_mul_f32 v[30:31], v[30:31], v[44:45]
	v_pk_mul_f32 v[26:27], v[26:27], v[46:47]
	v_pk_mul_f32 v[30:31], v[40:41], v[30:31]
	v_pk_mul_f32 v[40:41], v[42:43], v[26:27]
	v_cvt_pk_bf16_f32 v26, v24, v25
	v_mov_b64_e32 v[24:25], s[86:87]
	v_cvt_pk_bf16_f32 v27, v28, v29
	v_cvt_pk_bf16_f32 v29, v30, v31
	v_mad_i64_i32 v[30:31], s[10:11], v52, s90, v[24:25]
	v_cvt_pk_bf16_f32 v28, v40, v41
	v_lshl_add_u64 v[30:31], v[30:31], 0, v[112:113]
	global_store_dwordx4 v[30:31], v[26:29], off
	s_nop 0
	v_mov_b64_e32 v[30:31], 0
	v_mov_b32_e32 v26, 0
	v_mov_b32_e32 v27, 0
	v_mov_b32_e32 v28, 0
	v_mov_b32_dpp v26, v116 row_ror:1 row_mask:0xf bank_mask:0xf
	v_mov_b32_dpp v27, v117 row_ror:1 row_mask:0xf bank_mask:0xf
	v_mov_b32_e32 v29, 0
	v_mov_b32_dpp v26, v22 row_shr:1 row_mask:0xf bank_mask:0xf
	v_mov_b32_dpp v27, v23 row_shr:1 row_mask:0xf bank_mask:0xf
	v_mov_b32_dpp v28, v114 row_ror:1 row_mask:0xf bank_mask:0xf
	v_mov_b32_dpp v29, v115 row_ror:1 row_mask:0xf bank_mask:0xf
	v_mov_b32_dpp v30, v36 row_ror:15 row_mask:0xf bank_mask:0xf
	v_mov_b32_dpp v31, v37 row_ror:15 row_mask:0xf bank_mask:0xf
	v_pk_fma_f32 v[26:27], v[80:81], v[26:27], v[84:85]
	v_mov_b64_e32 v[40:41], 0
	v_mov_b32_dpp v28, v20 row_shr:1 row_mask:0xf bank_mask:0xf
	v_mov_b32_dpp v29, v21 row_shr:1 row_mask:0xf bank_mask:0xf
	v_mov_b32_dpp v30, v22 row_shl:1 row_mask:0xf bank_mask:0xf
	v_mov_b32_dpp v31, v23 row_shl:1 row_mask:0xf bank_mask:0xf
	v_pk_fma_f32 v[26:27], v[22:23], v[76:77], v[26:27]
	v_mov_b32_dpp v40, v38 row_ror:15 row_mask:0xf bank_mask:0xf
	v_mov_b32_dpp v41, v39 row_ror:15 row_mask:0xf bank_mask:0xf
	v_pk_fma_f32 v[28:29], v[82:83], v[28:29], v[86:87]
	v_pk_fma_f32 v[26:27], v[72:73], v[30:31], v[26:27]
	v_mov_b32_dpp v40, v20 row_shl:1 row_mask:0xf bank_mask:0xf
	v_mov_b32_dpp v41, v21 row_shl:1 row_mask:0xf bank_mask:0xf
	v_pk_fma_f32 v[28:29], v[20:21], v[78:79], v[28:29]
	v_pk_mul_f32 v[30:31], v[26:27], v[26:27]
	v_pk_fma_f32 v[28:29], v[74:75], v[40:41], v[28:29]
	v_pk_mul_f32 v[30:31], v[26:27], v[30:31]
	v_pk_mul_f32 v[40:41], v[28:29], v[28:29]
	v_pk_fma_f32 v[30:31], v[30:31], s[70:71], v[26:27] op_sel_hi:[1,0,1]
	v_pk_mul_f32 v[40:41], v[28:29], v[40:41]
	v_pk_mul_f32 v[30:31], v[30:31], s[72:73] op_sel_hi:[1,0]
	v_pk_fma_f32 v[40:41], v[40:41], s[70:71], v[28:29] op_sel_hi:[1,0,1]
	v_min_f32_e32 v30, 0x41e6d4ca, v30
	v_pk_mul_f32 v[40:41], v[40:41], s[72:73] op_sel_hi:[1,0]
	v_exp_f32_e32 v43, v30
	v_min_f32_e32 v30, 0x41e6d4ca, v31
	v_exp_f32_e32 v42, v30
	v_min_f32_e32 v30, 0x41e6d4ca, v40
	v_exp_f32_e32 v31, v30
	v_min_f32_e32 v30, 0x41e6d4ca, v41
	v_exp_f32_e32 v30, v30
	v_pk_add_f32 v[40:41], v[42:43], 1.0 op_sel_hi:[1,0]
	v_add_u32_e32 v46, 0xa0, v197
	v_pk_add_f32 v[30:31], v[30:31], 1.0 op_sel_hi:[1,0]
	v_mul_f32_e32 v42, v41, v40
	v_mul_f32_e32 v43, v31, v30
	v_mov_b32_dpp v96, v32 row_shl:1 row_mask:0xf bank_mask:0xf
	v_mul_f32_e32 v44, v42, v43
	v_rcp_f32_e32 v45, v44
	v_mov_b32_dpp v97, v33 row_shl:1 row_mask:0xf bank_mask:0xf
	v_mov_b32_dpp v98, v34 row_shl:1 row_mask:0xf bank_mask:0xf
	v_mov_b32_dpp v99, v35 row_shl:1 row_mask:0xf bank_mask:0xf
	v_mul_f32_e32 v44, v43, v45
	v_pk_mul_f32 v[40:41], v[40:41], v[44:45] op_sel_hi:[1,0]
	v_mul_f32_e32 v42, v42, v45
	v_pk_mul_f32 v[26:27], v[26:27], v[40:41]
	v_pk_mul_f32 v[30:31], v[30:31], v[42:43] op_sel_hi:[1,0]
	v_pk_mul_f32 v[12:13], v[12:13], v[26:27]
	v_mov_b32_e32 v26, 0
	v_mov_b32_e32 v27, 0
	v_pk_mul_f32 v[28:29], v[28:29], v[30:31]
	v_mov_b32_dpp v26, v110 row_ror:1 row_mask:0xf bank_mask:0xf
	v_mov_b32_dpp v27, v111 row_ror:1 row_mask:0xf bank_mask:0xf
	v_pk_mul_f32 v[14:15], v[14:15], v[28:29]
	v_mov_b64_e32 v[28:29], 0
	v_mov_b64_e32 v[30:31], 0
	v_mov_b32_dpp v26, v18 row_shr:1 row_mask:0xf bank_mask:0xf
	v_mov_b32_dpp v27, v19 row_shr:1 row_mask:0xf bank_mask:0xf
	v_mov_b32_dpp v28, v108 row_ror:1 row_mask:0xf bank_mask:0xf
	v_mov_b32_dpp v29, v109 row_ror:1 row_mask:0xf bank_mask:0xf
	v_mov_b32_dpp v30, v32 row_ror:15 row_mask:0xf bank_mask:0xf
	v_mov_b32_dpp v31, v33 row_ror:15 row_mask:0xf bank_mask:0xf
	v_pk_fma_f32 v[26:27], v[64:65], v[26:27], v[68:69]
	v_mov_b64_e32 v[40:41], 0
	v_mov_b32_dpp v28, v16 row_shr:1 row_mask:0xf bank_mask:0xf
	v_mov_b32_dpp v29, v17 row_shr:1 row_mask:0xf bank_mask:0xf
	v_mov_b32_dpp v30, v18 row_shl:1 row_mask:0xf bank_mask:0xf
	v_mov_b32_dpp v31, v19 row_shl:1 row_mask:0xf bank_mask:0xf
	v_pk_fma_f32 v[26:27], v[18:19], v[60:61], v[26:27]
	v_mov_b32_dpp v40, v34 row_ror:15 row_mask:0xf bank_mask:0xf
	v_mov_b32_dpp v41, v35 row_ror:15 row_mask:0xf bank_mask:0xf
	v_pk_fma_f32 v[28:29], v[66:67], v[28:29], v[70:71]
	v_pk_fma_f32 v[26:27], v[56:57], v[30:31], v[26:27]
	v_mov_b32_dpp v40, v16 row_shl:1 row_mask:0xf bank_mask:0xf
	v_mov_b32_dpp v41, v17 row_shl:1 row_mask:0xf bank_mask:0xf
	v_pk_fma_f32 v[28:29], v[16:17], v[62:63], v[28:29]
	v_pk_mul_f32 v[30:31], v[26:27], v[26:27]
	v_pk_fma_f32 v[28:29], v[58:59], v[40:41], v[28:29]
	v_pk_mul_f32 v[30:31], v[26:27], v[30:31]
	v_pk_mul_f32 v[40:41], v[28:29], v[28:29]
	v_pk_fma_f32 v[30:31], v[30:31], s[70:71], v[26:27] op_sel_hi:[1,0,1]
	v_pk_mul_f32 v[40:41], v[28:29], v[40:41]
	v_pk_mul_f32 v[30:31], v[30:31], s[72:73] op_sel_hi:[1,0]
	v_pk_fma_f32 v[40:41], v[40:41], s[70:71], v[28:29] op_sel_hi:[1,0,1]
	v_min_f32_e32 v30, 0x41e6d4ca, v30
	v_pk_mul_f32 v[40:41], v[40:41], s[72:73] op_sel_hi:[1,0]
	v_exp_f32_e32 v43, v30
	v_min_f32_e32 v30, 0x41e6d4ca, v31
	v_exp_f32_e32 v42, v30
	v_min_f32_e32 v30, 0x41e6d4ca, v40
	v_exp_f32_e32 v31, v30
	v_min_f32_e32 v30, 0x41e6d4ca, v41
	v_exp_f32_e32 v30, v30
	v_pk_add_f32 v[40:41], v[42:43], 1.0 op_sel_hi:[1,0]
	v_pk_mul_f32 v[0:1], v[0:1], v[194:195]
	v_pk_add_f32 v[30:31], v[30:31], 1.0 op_sel_hi:[1,0]
	v_mul_f32_e32 v42, v41, v40
	v_mul_f32_e32 v43, v31, v30
	s_nop 0
	v_mul_f32_e32 v44, v42, v43
	v_rcp_f32_e32 v45, v44
	s_nop 0
	v_mul_f32_e32 v44, v43, v45
	v_mul_f32_e32 v42, v42, v45
	v_pk_mul_f32 v[30:31], v[30:31], v[42:43] op_sel_hi:[1,0]
	v_pk_mul_f32 v[40:41], v[40:41], v[44:45] op_sel_hi:[1,0]
	v_pk_mul_f32 v[28:29], v[28:29], v[30:31]
	v_pk_mul_f32 v[26:27], v[26:27], v[40:41]
	v_pk_mul_f32 v[28:29], v[10:11], v[28:29]
	v_pk_mul_f32 v[10:11], v[8:9], v[26:27]
	v_cvt_pk_bf16_f32 v8, v12, v13
	v_mad_i64_i32 v[12:13], s[10:11], v46, s90, v[24:25]
	v_cvt_pk_bf16_f32 v9, v14, v15
	v_cvt_pk_bf16_f32 v10, v10, v11
	v_cvt_pk_bf16_f32 v11, v28, v29
	v_lshl_add_u64 v[12:13], v[12:13], 0, v[112:113]
	global_store_dwordx4 v[12:13], v[8:11], off
	v_add_u32_e32 v30, 0xb0, v197
	s_nop 0
	v_mov_b32_e32 v8, 0
	v_mov_b32_e32 v9, 0
	v_mov_b32_e32 v10, 0
	v_mov_b32_dpp v8, v22 row_ror:1 row_mask:0xf bank_mask:0xf
	v_mov_b32_dpp v9, v23 row_ror:1 row_mask:0xf bank_mask:0xf
	v_mov_b32_e32 v11, 0
	v_mov_b32_dpp v8, v36 row_shr:1 row_mask:0xf bank_mask:0xf
	v_mov_b32_dpp v9, v37 row_shr:1 row_mask:0xf bank_mask:0xf
	v_mov_b32_dpp v10, v20 row_ror:1 row_mask:0xf bank_mask:0xf
	v_mov_b32_dpp v11, v21 row_ror:1 row_mask:0xf bank_mask:0xf
	v_pk_fma_f32 v[8:9], v[80:81], v[8:9], v[84:85]
	v_mov_b32_dpp v10, v38 row_shr:1 row_mask:0xf bank_mask:0xf
	v_mov_b32_dpp v11, v39 row_shr:1 row_mask:0xf bank_mask:0xf
	v_pk_fma_f32 v[8:9], v[36:37], v[76:77], v[8:9]
	v_pk_fma_f32 v[10:11], v[82:83], v[10:11], v[86:87]
	v_pk_fma_f32 v[8:9], v[72:73], v[100:101], v[8:9]
	v_pk_fma_f32 v[10:11], v[38:39], v[78:79], v[10:11]
	v_pk_mul_f32 v[12:13], v[8:9], v[8:9]
	v_pk_fma_f32 v[10:11], v[74:75], v[102:103], v[10:11]
	v_pk_mul_f32 v[12:13], v[8:9], v[12:13]
	v_pk_mul_f32 v[14:15], v[10:11], v[10:11]
	v_pk_fma_f32 v[12:13], v[12:13], s[70:71], v[8:9] op_sel_hi:[1,0,1]
	v_pk_mul_f32 v[14:15], v[10:11], v[14:15]
	v_pk_mul_f32 v[12:13], v[12:13], s[72:73] op_sel_hi:[1,0]
	v_pk_fma_f32 v[14:15], v[14:15], s[70:71], v[10:11] op_sel_hi:[1,0,1]
	v_min_f32_e32 v12, 0x41e6d4ca, v12
	v_pk_mul_f32 v[14:15], v[14:15], s[72:73] op_sel_hi:[1,0]
	v_exp_f32_e32 v21, v12
	v_min_f32_e32 v12, 0x41e6d4ca, v13
	v_exp_f32_e32 v20, v12
	v_min_f32_e32 v12, 0x41e6d4ca, v14
	v_exp_f32_e32 v13, v12
	v_min_f32_e32 v12, 0x41e6d4ca, v15
	v_exp_f32_e32 v12, v12
	v_pk_add_f32 v[14:15], v[20:21], 1.0 op_sel_hi:[1,0]
	v_pk_add_f32 v[12:13], v[12:13], 1.0 op_sel_hi:[1,0]
	v_mul_f32_e32 v20, v15, v14
	v_mul_f32_e32 v21, v13, v12
	s_nop 0
	v_mul_f32_e32 v22, v20, v21
	v_rcp_f32_e32 v23, v22
	s_nop 0
	v_mul_f32_e32 v20, v20, v23
	v_pk_mul_f32 v[12:13], v[12:13], v[20:21] op_sel_hi:[1,0]
	v_mul_f32_e32 v22, v21, v23
	v_pk_mul_f32 v[12:13], v[10:11], v[12:13]
	v_pk_mul_f32 v[14:15], v[14:15], v[22:23] op_sel_hi:[1,0]
	v_pk_mul_f32 v[20:21], v[6:7], v[12:13]
	v_mov_b32_e32 v12, 0
	v_mov_b32_e32 v13, 0
	v_pk_mul_f32 v[14:15], v[8:9], v[14:15]
	v_mov_b32_dpp v12, v18 row_ror:1 row_mask:0xf bank_mask:0xf
	v_mov_b32_dpp v13, v19 row_ror:1 row_mask:0xf bank_mask:0xf
	v_pk_mul_f32 v[22:23], v[4:5], v[14:15]
	v_mov_b32_e32 v14, 0
	v_mov_b32_e32 v15, 0
	v_mov_b32_dpp v12, v32 row_shr:1 row_mask:0xf bank_mask:0xf
	v_mov_b32_dpp v13, v33 row_shr:1 row_mask:0xf bank_mask:0xf
	v_mov_b32_dpp v14, v16 row_ror:1 row_mask:0xf bank_mask:0xf
	v_mov_b32_dpp v15, v17 row_ror:1 row_mask:0xf bank_mask:0xf
	v_pk_fma_f32 v[12:13], v[64:65], v[12:13], v[68:69]
	v_mov_b32_dpp v14, v34 row_shr:1 row_mask:0xf bank_mask:0xf
	v_mov_b32_dpp v15, v35 row_shr:1 row_mask:0xf bank_mask:0xf
	v_pk_fma_f32 v[12:13], v[32:33], v[60:61], v[12:13]
	v_pk_fma_f32 v[14:15], v[66:67], v[14:15], v[70:71]
	v_pk_fma_f32 v[12:13], v[56:57], v[96:97], v[12:13]
	v_pk_fma_f32 v[14:15], v[34:35], v[62:63], v[14:15]
	v_pk_mul_f32 v[16:17], v[12:13], v[12:13]
	v_pk_fma_f32 v[14:15], v[58:59], v[98:99], v[14:15]
	v_pk_mul_f32 v[16:17], v[12:13], v[16:17]
	v_pk_mul_f32 v[18:19], v[14:15], v[14:15]
	v_pk_fma_f32 v[16:17], v[16:17], s[70:71], v[12:13] op_sel_hi:[1,0,1]
	v_pk_mul_f32 v[18:19], v[14:15], v[18:19]
	v_pk_mul_f32 v[16:17], v[16:17], s[72:73] op_sel_hi:[1,0]
	v_pk_fma_f32 v[18:19], v[18:19], s[70:71], v[14:15] op_sel_hi:[1,0,1]
	v_min_f32_e32 v16, 0x41e6d4ca, v16
	v_pk_mul_f32 v[18:19], v[18:19], s[72:73] op_sel_hi:[1,0]
	v_exp_f32_e32 v27, v16
	v_min_f32_e32 v16, 0x41e6d4ca, v17
	v_exp_f32_e32 v26, v16
	v_min_f32_e32 v16, 0x41e6d4ca, v18
	v_exp_f32_e32 v17, v16
	v_min_f32_e32 v16, 0x41e6d4ca, v19
	v_exp_f32_e32 v16, v16
	v_pk_add_f32 v[18:19], v[26:27], 1.0 op_sel_hi:[1,0]
	v_pk_add_f32 v[16:17], v[16:17], 1.0 op_sel_hi:[1,0]
	v_mul_f32_e32 v26, v19, v18
	v_mul_f32_e32 v27, v17, v16
	s_nop 0
	v_mul_f32_e32 v28, v26, v27
	v_rcp_f32_e32 v29, v28
	s_nop 0
	v_mul_f32_e32 v28, v27, v29
	v_mul_f32_e32 v26, v26, v29
	v_pk_mul_f32 v[16:17], v[16:17], v[26:27] op_sel_hi:[1,0]
	v_pk_mul_f32 v[18:19], v[18:19], v[28:29] op_sel_hi:[1,0]
	v_pk_mul_f32 v[16:17], v[14:15], v[16:17]
	v_pk_mul_f32 v[18:19], v[12:13], v[18:19]
	v_pk_mul_f32 v[26:27], v[2:3], v[16:17]
	v_pk_mul_f32 v[18:19], v[0:1], v[18:19]
	v_cvt_pk_bf16_f32 v17, v20, v21
	v_mad_i64_i32 v[20:21], s[10:11], v30, s90, v[24:25]
	v_cvt_pk_bf16_f32 v16, v22, v23
	v_cvt_pk_bf16_f32 v18, v18, v19
	v_cvt_pk_bf16_f32 v19, v26, v27
	v_lshl_add_u64 v[20:21], v[20:21], 0, v[112:113]
	global_store_dwordx4 v[20:21], v[16:19], off
	s_and_saveexec_b64 s[10:11], s[64:65]
	s_cbranch_execz .LBB0_784
	s_add_u32 s14, s4, s14
	s_addc_u32 s15, s5, s12
	v_lshl_add_u64 v[16:17], v[192:193], 2, s[14:15]
	global_store_dwordx4 v[16:17], v[8:11], off
	s_nop 1
	v_add_co_u32_e32 v8, vcc, 0x2000, v16
	s_nop 1
	v_addc_co_u32_e32 v9, vcc, 0, v17, vcc
	v_add_co_u32_e32 v10, vcc, 0x5000, v16
	global_store_dwordx4 v[8:9], v[36:39], off offset:3072
	s_nop 0
	v_addc_co_u32_e32 v11, vcc, 0, v17, vcc
	global_store_dwordx4 v[10:11], v[4:7], off offset:2048
	global_store_dwordx4 v[16:17], v[12:15], off offset:16
	global_store_dwordx4 v[8:9], v[32:35], off offset:3088
	global_store_dwordx4 v[10:11], v[0:3], off offset:2064
